# GEMM1 epilogue: 8 row-stat loads hoisted before the K-loop, 8 vmcnt(0) drains removed
# speedup vs baseline: 1.0080x; 1.0080x over previous
; __device__ __forceinline__ float row_rs(const float* PS, int row, int fq) { return rsqrtf(PS[row] * (1.0f / 1024.0f) + 1e-6f); }
;     __device__ __forceinline__ void operator()(const f32x4 (&acc)[2][2][4][2], const Unit& u, int wr, int wc, int fr, int fq) const {
;     ...
;             for (int m = 0; m < 4; ++m) { const int row = row0 + ai * HALF + m * 16; const float rs = row_rs(PS, row, fq);
; template <class Epi, class Sched, bool ALIGN_EPI = false, bool SP2 = false>
; __device__ __forceinline__ void gemm_phase(PG8_LAS unsigned char* lds, const Gemm g, const Sched& S, const Epi& E, const int tid) {
;     ...
;         for (int a = 0; a < 2; ++a)
; #pragma unroll
;             for (int b = 0; b < 2; ++b)
; #pragma unroll
;                 for (int m = 0; m < 4; ++m)
; #pragma unroll
;                     for (int n = 0; n < 2; ++n) acc[a][b][m][n] = (f32x4){0.f, 0.f, 0.f, 0.f};
;         cur = nxt; cA = nA; cB = nB; ++ui;
.LBB0_301:
	s_ashr_i32 s57, s56, 31
	s_lshl_b64 s[30:31], s[56:57], 19
	s_add_u32 s58, s25, s30
	s_addc_u32 s59, s24, s31
	s_and_b64 s[30:31], s[40:41], exec
	s_cselect_b32 s22, s59, s19
	s_cselect_b32 s30, s58, s18
	s_ashr_i32 s55, s54, 31
	s_lshl_b64 s[34:35], s[54:55], 19
	s_add_u32 s60, s26, s34
	s_addc_u32 s61, s27, s35
	s_and_b64 s[34:35], s[40:41], exec
	s_cselect_b32 s31, s61, s47
	s_cselect_b32 s43, s60, s46
	s_add_u32 s18, s18, 0x40080
	s_addc_u32 s19, s19, 0
	s_add_u32 s45, s46, 0x100
	v_mov_b32_e32 v4, 0
	s_addc_u32 s55, s47, 0
	s_mov_b32 s57, -2
	v_mov_b32_e32 v5, v4
	v_mov_b32_e32 v6, v4
	v_mov_b32_e32 v7, v4
	v_mov_b32_e32 v8, v4
	v_mov_b32_e32 v9, v4
	v_mov_b32_e32 v10, v4
	v_mov_b32_e32 v11, v4
	v_mov_b32_e32 v20, v4
	v_mov_b32_e32 v21, v4
	v_mov_b32_e32 v22, v4
	v_mov_b32_e32 v23, v4
	v_mov_b32_e32 v24, v4
	v_mov_b32_e32 v25, v4
	v_mov_b32_e32 v26, v4
	v_mov_b32_e32 v27, v4
	v_mov_b32_e32 v36, v4
	v_mov_b32_e32 v37, v4
	v_mov_b32_e32 v38, v4
	v_mov_b32_e32 v39, v4
	v_mov_b32_e32 v40, v4
	v_mov_b32_e32 v41, v4
	v_mov_b32_e32 v42, v4
	v_mov_b32_e32 v43, v4
	v_mov_b32_e32 v52, v4
	v_mov_b32_e32 v53, v4
	v_mov_b32_e32 v54, v4
	v_mov_b32_e32 v55, v4
	v_mov_b32_e32 v56, v4
	v_mov_b32_e32 v57, v4
	v_mov_b32_e32 v58, v4
	v_mov_b32_e32 v59, v4
	v_mov_b32_e32 v12, v4
	v_mov_b32_e32 v13, v4
	v_mov_b32_e32 v14, v4
	v_mov_b32_e32 v15, v4
	v_mov_b32_e32 v16, v4
	v_mov_b32_e32 v17, v4
	v_mov_b32_e32 v18, v4
	v_mov_b32_e32 v19, v4
	v_mov_b32_e32 v28, v4
	v_mov_b32_e32 v29, v4
	v_mov_b32_e32 v30, v4
	v_mov_b32_e32 v31, v4
	v_mov_b32_e32 v32, v4
	v_mov_b32_e32 v33, v4
	v_mov_b32_e32 v34, v4
	v_mov_b32_e32 v35, v4
	v_mov_b32_e32 v44, v4
	v_mov_b32_e32 v45, v4
	v_mov_b32_e32 v46, v4
	v_mov_b32_e32 v47, v4
	v_mov_b32_e32 v48, v4
	v_mov_b32_e32 v49, v4
	v_mov_b32_e32 v50, v4
	v_mov_b32_e32 v51, v4
	v_mov_b32_e32 v60, v4
	v_mov_b32_e32 v61, v4
	v_mov_b32_e32 v62, v4
	v_mov_b32_e32 v63, v4
	v_mov_b32_e32 v64, v4
	v_mov_b32_e32 v65, v4
	v_mov_b32_e32 v66, v4
	v_mov_b32_e32 v67, v4
	v_mov_b32_e32 v68, v4
	v_mov_b32_e32 v69, v4
	v_mov_b32_e32 v70, v4
	v_mov_b32_e32 v71, v4
	v_mov_b32_e32 v72, v4
	v_mov_b32_e32 v73, v4
	v_mov_b32_e32 v74, v4
	v_mov_b32_e32 v75, v4
	v_mov_b32_e32 v84, v4
	v_mov_b32_e32 v85, v4
	v_mov_b32_e32 v86, v4
	v_mov_b32_e32 v87, v4
	v_mov_b32_e32 v88, v4
	v_mov_b32_e32 v89, v4
	v_mov_b32_e32 v90, v4
	v_mov_b32_e32 v91, v4
	v_mov_b32_e32 v100, v4
	v_mov_b32_e32 v101, v4
	v_mov_b32_e32 v102, v4
	v_mov_b32_e32 v103, v4
	v_mov_b32_e32 v104, v4
	v_mov_b32_e32 v105, v4
	v_mov_b32_e32 v106, v4
	v_mov_b32_e32 v107, v4
	v_mov_b32_e32 v116, v4
	v_mov_b32_e32 v117, v4
	v_mov_b32_e32 v118, v4
	v_mov_b32_e32 v119, v4
	v_mov_b32_e32 v120, v4
	v_mov_b32_e32 v121, v4
	v_mov_b32_e32 v122, v4
	v_mov_b32_e32 v123, v4
	v_mov_b32_e32 v76, v4
	v_mov_b32_e32 v77, v4
	v_mov_b32_e32 v78, v4
	v_mov_b32_e32 v79, v4
	v_mov_b32_e32 v80, v4
	v_mov_b32_e32 v81, v4
	v_mov_b32_e32 v82, v4
	v_mov_b32_e32 v83, v4
	v_mov_b32_e32 v92, v4
	v_mov_b32_e32 v93, v4
	v_mov_b32_e32 v94, v4
	v_mov_b32_e32 v95, v4
	v_mov_b32_e32 v96, v4
	v_mov_b32_e32 v97, v4
	v_mov_b32_e32 v98, v4
	v_mov_b32_e32 v99, v4
	v_mov_b32_e32 v108, v4
	v_mov_b32_e32 v109, v4
	v_mov_b32_e32 v110, v4
	v_mov_b32_e32 v111, v4
	v_mov_b32_e32 v112, v4
	v_mov_b32_e32 v113, v4
	v_mov_b32_e32 v114, v4
	v_mov_b32_e32 v115, v4
	v_mov_b32_e32 v124, v4
	v_mov_b32_e32 v125, v4
	v_mov_b32_e32 v126, v4
	v_mov_b32_e32 v127, v4
	v_mov_b32_e32 v128, v4
	v_mov_b32_e32 v129, v4
	v_mov_b32_e32 v130, v4
	v_mov_b32_e32 v131, v4
	v_lshl_add_u32 v244, s42, 8, v3
	v_ashrrev_i32_e32 v245, 31, v244
	v_lshl_add_u64 v[244:245], v[244:245], 2, s[50:51]
	global_load_dword v226, v[244:245], off
	global_load_dword v227, v[244:245], off offset:64
	global_load_dword v228, v[244:245], off offset:128
	global_load_dword v229, v[244:245], off offset:192
	global_load_dword v230, v[244:245], off offset:512
	global_load_dword v231, v[244:245], off offset:576
	global_load_dword v232, v[244:245], off offset:640
	global_load_dword v233, v[244:245], off offset:704

; __device__ __forceinline__ float fexp2(float x) { return __builtin_amdgcn_exp2f(x); }
; __device__ __forceinline__ float frcp(float x) { return __builtin_amdgcn_rcpf(x); }
; __device__ __forceinline__ float gelu_tanh(float x) { const float in = x * (1.0f + 0.044715f * x * x); return x * frcp(1.0f + fexp2(-2.302208198f * in)); }
; __device__ __forceinline__ float row_rs(const float* PS, int row, int fq) { return rsqrtf(PS[row] * (1.0f / 1024.0f) + 1e-6f); }
;     __device__ __forceinline__ static unsigned q8(float s) { return (unsigned)fminf(s * 256.0f, 255.0f); }
;     __device__ __forceinline__ void operator()(const f32x4 (&acc)[2][2][4][2], const Unit& u, int wr, int wc, int fr, int fq) const {
;     ...
;             for (int m = 0; m < 4; ++m) { const int row = row0 + ai * HALF + m * 16; const float rs = row_rs(PS, row, fq);
;                 if (sig) {
;                     unsigned w[4];
; #pragma unroll
;                     for (int bj = 0; bj < 2; ++bj) { const f32x4 v0 = acc[ai][bj][m][0] * rs, v1 = acc[ai][bj][m][1] * rs; unsigned b[8];
; #pragma unroll
;                         for (int j = 0; j < 4; ++j) { b[j] = q8(frcp(1.0f + fexp2(-1.4426950409f * v0[j]))); b[4 + j] = q8(frcp(1.0f + fexp2(-1.4426950409f * v1[j]))); }
;                         w[2 * bj] = b[0] | (b[1] << 8) | (b[2] << 16) | (b[3] << 24); w[2 * bj + 1] = b[4] | (b[5] << 8) | (b[6] << 16) | (b[7] << 24); }
;                     u32x4 wv; wv.x = w[0]; wv.y = w[1]; wv.z = w[2]; wv.w = w[3];
;                     *(u32x4*)((unsigned char*)O + (size_t)row * (2 * ldc) + 3584 + 2 * ((u.pn - 7) * 128 + wc * 32 + 8 * fq)) = wv;
;                 } else {
;                     bf16_t* rowp = O + (size_t)row * ldc + col0;
; #pragma unroll
;                     for (int bj = 0; bj < 2; ++bj) { f32x4 v0 = acc[ai][bj][m][0] * rs, v1 = acc[ai][bj][m][1] * rs;
;                         if (act) {
; #pragma unroll
;                             for (int j = 0; j < 4; ++j) { v0[j] = gelu_tanh(v0[j]); v1[j] = gelu_tanh(v1[j]); } }
.LBB0_305:
	v_lshl_add_u32 v146, s42, 8, v3
	v_ashrrev_i32_e32 v147, 31, v146
	v_lshl_add_u64 v[148:149], v[146:147], 2, s[50:51]
	v_mov_b32_e32 v144, v226
	s_lshl_b32 s22, s44, 8
	s_add_i32 s18, s44, -3
	s_cmp_lt_u32 s18, 4
	s_cselect_b64 s[34:35], -1, 0
	s_cmp_lt_i32 s44, 7
	v_or_b32_e32 v142, s22, v161
	s_cselect_b64 s[18:19], -1, 0
	v_ashrrev_i32_e32 v143, 31, v142
	s_mov_b64 s[44:45], -1
	v_fmamk_f32 v144, v144, 0x3a800000, v196
	v_cmp_gt_f32_e32 vcc, s13, v144
	v_mul_f32_e32 v145, 0x4b800000, v144
	s_nop 0
	v_cndmask_b32_e32 v144, v144, v145, vcc
	v_rsq_f32_e32 v144, v144
	s_nop 0
	v_mul_f32_e32 v145, 0x45800000, v144
	v_cndmask_b32_e32 v150, v144, v145, vcc
	v_cndmask_b32_e64 v144, 0, 1, s[34:35]
	s_and_b64 vcc, exec, s[18:19]
	v_cmp_ne_u32_e64 s[42:43], 1, v144
	s_cbranch_vccz .LBB0_311
	v_pk_mul_f32 v[152:153], v[130:131], v[150:151] op_sel_hi:[1,0]
	v_pk_mul_f32 v[156:157], v[128:129], v[150:151] op_sel_hi:[1,0]
	v_pk_mul_f32 v[154:155], v[126:127], v[150:151] op_sel_hi:[1,0]
	s_and_b64 vcc, exec, s[42:43]
	v_pk_mul_f32 v[158:159], v[124:125], v[150:151] op_sel_hi:[1,0]
	s_cbranch_vccnz .LBB0_308
	v_mul_f32_e32 v147, 0x3d372713, v159
	v_fma_f32 v147, v159, v147, 1.0
	v_mul_f32_e32 v147, v159, v147
	v_mul_f32_e32 v147, 0xc0135761, v147
	v_exp_f32_e32 v147, v147
	v_mul_f32_e32 v145, 0x3d372713, v158
	v_fma_f32 v145, v158, v145, 1.0
	v_mul_f32_e32 v145, v158, v145
	v_mul_f32_e32 v145, 0xc0135761, v145
	v_add_f32_e32 v147, 1.0, v147
	v_exp_f32_e32 v145, v145
	v_rcp_f32_e32 v165, v147
	v_mul_f32_e32 v147, 0x3d372713, v152
	v_fma_f32 v147, v152, v147, 1.0
	v_mul_f32_e32 v147, v152, v147
	v_mul_f32_e32 v147, 0xc0135761, v147
	v_add_f32_e32 v145, 1.0, v145
	v_exp_f32_e32 v147, v147
	v_mul_f32_e32 v144, 0x3d372713, v156
	v_rcp_f32_e32 v164, v145
	v_mul_f32_e32 v145, 0x3d372713, v157
	v_fma_f32 v144, v156, v144, 1.0
	v_fma_f32 v145, v157, v145, 1.0
	v_mul_f32_e32 v144, v156, v144
	v_mul_f32_e32 v145, v157, v145
	v_mul_f32_e32 v144, 0xc0135761, v144
	v_mul_f32_e32 v145, 0xc0135761, v145
	v_add_f32_e32 v147, 1.0, v147
	v_exp_f32_e32 v144, v144
	v_exp_f32_e32 v145, v145
	v_rcp_f32_e32 v166, v147
	v_mul_f32_e32 v147, 0x3d372713, v154
	v_fma_f32 v147, v154, v147, 1.0
	v_mul_f32_e32 v147, v154, v147
	v_mul_f32_e32 v147, 0xc0135761, v147
	v_add_f32_e32 v144, 1.0, v144
	v_add_f32_e32 v145, 1.0, v145
	v_exp_f32_e32 v147, v147
	v_rcp_f32_e32 v144, v144
	v_rcp_f32_e32 v145, v145
	v_pk_mul_f32 v[158:159], v[158:159], v[164:165]
	v_add_f32_e32 v147, 1.0, v147
	v_rcp_f32_e32 v168, v147
	v_mul_f32_e32 v147, 0x3d372713, v153
	v_pk_mul_f32 v[156:157], v[156:157], v[144:145]
	v_mul_f32_e32 v144, 0x3d372713, v155
	v_fma_f32 v147, v153, v147, 1.0
	v_fma_f32 v144, v155, v144, 1.0
	v_mul_f32_e32 v147, v153, v147
	v_mul_f32_e32 v144, v155, v144
	v_mul_f32_e32 v147, 0xc0135761, v147
	v_mul_f32_e32 v144, 0xc0135761, v144
	v_exp_f32_e32 v147, v147
	v_exp_f32_e32 v144, v144
	v_add_f32_e32 v147, 1.0, v147
	v_add_f32_e32 v144, 1.0, v144
	v_rcp_f32_e32 v167, v147
	v_rcp_f32_e32 v169, v144
	v_pk_mul_f32 v[152:153], v[152:153], v[166:167]
	v_pk_mul_f32 v[154:155], v[154:155], v[168:169]

; __device__ __forceinline__ float fexp2(float x) { return __builtin_amdgcn_exp2f(x); }
; __device__ __forceinline__ float frcp(float x) { return __builtin_amdgcn_rcpf(x); }
; __device__ __forceinline__ float gelu_tanh(float x) { const float in = x * (1.0f + 0.044715f * x * x); return x * frcp(1.0f + fexp2(-2.302208198f * in)); }
; __device__ __forceinline__ float row_rs(const float* PS, int row, int fq) { return rsqrtf(PS[row] * (1.0f / 1024.0f) + 1e-6f); }
;     __device__ __forceinline__ static unsigned q8(float s) { return (unsigned)fminf(s * 256.0f, 255.0f); }
;     __device__ __forceinline__ void operator()(const f32x4 (&acc)[2][2][4][2], const Unit& u, int wr, int wc, int fr, int fq) const {
;     ...
;             for (int m = 0; m < 4; ++m) { const int row = row0 + ai * HALF + m * 16; const float rs = row_rs(PS, row, fq);
;                 if (sig) {
;                     unsigned w[4];
; #pragma unroll
;                     for (int bj = 0; bj < 2; ++bj) { const f32x4 v0 = acc[ai][bj][m][0] * rs, v1 = acc[ai][bj][m][1] * rs; unsigned b[8];
; #pragma unroll
;                         for (int j = 0; j < 4; ++j) { b[j] = q8(frcp(1.0f + fexp2(-1.4426950409f * v0[j]))); b[4 + j] = q8(frcp(1.0f + fexp2(-1.4426950409f * v1[j]))); }
;                         w[2 * bj] = b[0] | (b[1] << 8) | (b[2] << 16) | (b[3] << 24); w[2 * bj + 1] = b[4] | (b[5] << 8) | (b[6] << 16) | (b[7] << 24); }
;                     u32x4 wv; wv.x = w[0]; wv.y = w[1]; wv.z = w[2]; wv.w = w[3];
;                     *(u32x4*)((unsigned char*)O + (size_t)row * (2 * ldc) + 3584 + 2 * ((u.pn - 7) * 128 + wc * 32 + 8 * fq)) = wv;
;                 } else {
;                     bf16_t* rowp = O + (size_t)row * ldc + col0;
; #pragma unroll
;                     for (int bj = 0; bj < 2; ++bj) { f32x4 v0 = acc[ai][bj][m][0] * rs, v1 = acc[ai][bj][m][1] * rs;
;                         if (act) {
; #pragma unroll
;                             for (int j = 0; j < 4; ++j) { v0[j] = gelu_tanh(v0[j]); v1[j] = gelu_tanh(v1[j]); } }
.LBB0_313:
	v_mov_b32_e32 v116, v227
	v_or_b32_e32 v128, 16, v146
	s_andn2_b64 vcc, exec, s[18:19]
	v_fmamk_f32 v116, v116, 0x3a800000, v196
	v_mul_f32_e32 v117, 0x4b800000, v116
	v_cmp_gt_f32_e64 s[46:47], s13, v116
	s_nop 1
	v_cndmask_b32_e64 v116, v116, v117, s[46:47]
	v_rsq_f32_e32 v116, v116
	v_cndmask_b32_e64 v117, 0, 1, s[18:19]
	v_cmp_ne_u32_e64 s[44:45], 1, v117
	s_mov_b64 s[18:19], -1
	v_mul_f32_e32 v117, 0x45800000, v116
	v_cndmask_b32_e64 v116, v116, v117, s[46:47]
	s_cbranch_vccnz .LBB0_319
	v_pk_mul_f32 v[120:121], v[114:115], v[116:117] op_sel_hi:[1,0]
	v_pk_mul_f32 v[124:125], v[112:113], v[116:117] op_sel_hi:[1,0]
	v_pk_mul_f32 v[122:123], v[110:111], v[116:117] op_sel_hi:[1,0]
	s_and_b64 vcc, exec, s[42:43]
	v_pk_mul_f32 v[126:127], v[108:109], v[116:117] op_sel_hi:[1,0]
	s_cbranch_vccnz .LBB0_316
	v_mul_f32_e32 v117, 0x3d372713, v124
	v_fma_f32 v117, v124, v117, 1.0
	v_mul_f32_e32 v117, v124, v117
	v_mul_f32_e32 v117, 0xc0135761, v117
	v_exp_f32_e32 v117, v117
	s_nop 0
	v_add_f32_e32 v117, 1.0, v117
	v_rcp_f32_e32 v118, v117
	v_mul_f32_e32 v117, 0x3d372713, v126
	v_fma_f32 v117, v126, v117, 1.0
	v_mul_f32_e32 v117, v126, v117
	v_mul_f32_e32 v117, 0xc0135761, v117
	v_exp_f32_e32 v117, v117
	s_nop 0
	v_add_f32_e32 v117, 1.0, v117
	v_rcp_f32_e32 v130, v117
	v_mul_f32_e32 v117, 0x3d372713, v125
	v_fma_f32 v117, v125, v117, 1.0
	v_mul_f32_e32 v117, v125, v117
	v_mul_f32_e32 v117, 0xc0135761, v117
	v_exp_f32_e32 v117, v117
	s_nop 0
	v_add_f32_e32 v117, 1.0, v117
	v_rcp_f32_e32 v119, v117
	v_mul_f32_e32 v117, 0x3d372713, v127
	v_fma_f32 v117, v127, v117, 1.0
	v_mul_f32_e32 v117, v127, v117
	v_mul_f32_e32 v117, 0xc0135761, v117
	v_exp_f32_e32 v117, v117
	v_pk_mul_f32 v[124:125], v[124:125], v[118:119]
	v_add_f32_e32 v117, 1.0, v117
	v_rcp_f32_e32 v131, v117
	v_mul_f32_e32 v117, 0x3d372713, v120
	v_fma_f32 v117, v120, v117, 1.0
	v_mul_f32_e32 v117, v120, v117
	v_mul_f32_e32 v117, 0xc0135761, v117
	v_exp_f32_e32 v117, v117
	v_pk_mul_f32 v[126:127], v[126:127], v[130:131]
	v_add_f32_e32 v117, 1.0, v117
	v_rcp_f32_e32 v150, v117
	v_mul_f32_e32 v117, 0x3d372713, v122
	v_fma_f32 v117, v122, v117, 1.0
	v_mul_f32_e32 v117, v122, v117
	v_mul_f32_e32 v117, 0xc0135761, v117
	v_exp_f32_e32 v117, v117
	s_nop 0
	v_add_f32_e32 v117, 1.0, v117
	v_rcp_f32_e32 v152, v117
	v_mul_f32_e32 v117, 0x3d372713, v121
	v_fma_f32 v117, v121, v117, 1.0
	v_mul_f32_e32 v117, v121, v117
	v_mul_f32_e32 v117, 0xc0135761, v117
	v_exp_f32_e32 v117, v117
	s_nop 0
	v_add_f32_e32 v117, 1.0, v117
	v_rcp_f32_e32 v151, v117
	v_mul_f32_e32 v117, 0x3d372713, v123
	v_fma_f32 v117, v123, v117, 1.0
	v_mul_f32_e32 v117, v123, v117
	v_mul_f32_e32 v117, 0xc0135761, v117
	v_exp_f32_e32 v117, v117
	v_pk_mul_f32 v[120:121], v[120:121], v[150:151]
	v_add_f32_e32 v117, 1.0, v117
	v_rcp_f32_e32 v153, v117
	s_nop 0
	v_pk_mul_f32 v[122:123], v[122:123], v[152:153]

; __device__ __forceinline__ float fexp2(float x) { return __builtin_amdgcn_exp2f(x); }
; __device__ __forceinline__ float frcp(float x) { return __builtin_amdgcn_rcpf(x); }
; __device__ __forceinline__ float gelu_tanh(float x) { const float in = x * (1.0f + 0.044715f * x * x); return x * frcp(1.0f + fexp2(-2.302208198f * in)); }
; __device__ __forceinline__ float row_rs(const float* PS, int row, int fq) { return rsqrtf(PS[row] * (1.0f / 1024.0f) + 1e-6f); }
;     __device__ __forceinline__ static unsigned q8(float s) { return (unsigned)fminf(s * 256.0f, 255.0f); }
;     __device__ __forceinline__ void operator()(const f32x4 (&acc)[2][2][4][2], const Unit& u, int wr, int wc, int fr, int fq) const {
;     ...
;             for (int m = 0; m < 4; ++m) { const int row = row0 + ai * HALF + m * 16; const float rs = row_rs(PS, row, fq);
;                 if (sig) {
;                     unsigned w[4];
; #pragma unroll
;                     for (int bj = 0; bj < 2; ++bj) { const f32x4 v0 = acc[ai][bj][m][0] * rs, v1 = acc[ai][bj][m][1] * rs; unsigned b[8];
; #pragma unroll
;                         for (int j = 0; j < 4; ++j) { b[j] = q8(frcp(1.0f + fexp2(-1.4426950409f * v0[j]))); b[4 + j] = q8(frcp(1.0f + fexp2(-1.4426950409f * v1[j]))); }
;                         w[2 * bj] = b[0] | (b[1] << 8) | (b[2] << 16) | (b[3] << 24); w[2 * bj + 1] = b[4] | (b[5] << 8) | (b[6] << 16) | (b[7] << 24); }
;                     u32x4 wv; wv.x = w[0]; wv.y = w[1]; wv.z = w[2]; wv.w = w[3];
;                     *(u32x4*)((unsigned char*)O + (size_t)row * (2 * ldc) + 3584 + 2 * ((u.pn - 7) * 128 + wc * 32 + 8 * fq)) = wv;
;                 } else {
;                     bf16_t* rowp = O + (size_t)row * ldc + col0;
; #pragma unroll
;                     for (int bj = 0; bj < 2; ++bj) { f32x4 v0 = acc[ai][bj][m][0] * rs, v1 = acc[ai][bj][m][1] * rs;
;                         if (act) {
; #pragma unroll
;                             for (int j = 0; j < 4; ++j) { v0[j] = gelu_tanh(v0[j]); v1[j] = gelu_tanh(v1[j]); } }
.LBB0_321:
	v_mov_b32_e32 v100, v228
	v_or_b32_e32 v112, 32, v146
	s_and_b64 vcc, exec, s[44:45]
	s_mov_b64 s[18:19], -1
	v_fmamk_f32 v100, v100, 0x3a800000, v196
	v_mul_f32_e32 v101, 0x4b800000, v100
	v_cmp_gt_f32_e64 s[46:47], s13, v100
	s_nop 1
	v_cndmask_b32_e64 v100, v100, v101, s[46:47]
	v_rsq_f32_e32 v100, v100
	s_nop 0
	v_mul_f32_e32 v101, 0x45800000, v100
	v_cndmask_b32_e64 v100, v100, v101, s[46:47]
	s_cbranch_vccnz .LBB0_327
	v_pk_mul_f32 v[104:105], v[98:99], v[100:101] op_sel_hi:[1,0]
	v_pk_mul_f32 v[108:109], v[96:97], v[100:101] op_sel_hi:[1,0]
	v_pk_mul_f32 v[106:107], v[94:95], v[100:101] op_sel_hi:[1,0]
	s_and_b64 vcc, exec, s[42:43]
	v_pk_mul_f32 v[110:111], v[92:93], v[100:101] op_sel_hi:[1,0]
	s_cbranch_vccnz .LBB0_324
	v_mul_f32_e32 v101, 0x3d372713, v108
	v_fma_f32 v101, v108, v101, 1.0
	v_mul_f32_e32 v101, v108, v101
	v_mul_f32_e32 v101, 0xc0135761, v101
	v_exp_f32_e32 v101, v101
	s_nop 0
	v_add_f32_e32 v101, 1.0, v101
	v_rcp_f32_e32 v102, v101
	v_mul_f32_e32 v101, 0x3d372713, v110
	v_fma_f32 v101, v110, v101, 1.0
	v_mul_f32_e32 v101, v110, v101
	v_mul_f32_e32 v101, 0xc0135761, v101
	v_exp_f32_e32 v101, v101
	s_nop 0
	v_add_f32_e32 v101, 1.0, v101
	v_rcp_f32_e32 v114, v101
	v_mul_f32_e32 v101, 0x3d372713, v109
	v_fma_f32 v101, v109, v101, 1.0
	v_mul_f32_e32 v101, v109, v101
	v_mul_f32_e32 v101, 0xc0135761, v101
	v_exp_f32_e32 v101, v101
	s_nop 0
	v_add_f32_e32 v101, 1.0, v101
	v_rcp_f32_e32 v103, v101
	v_mul_f32_e32 v101, 0x3d372713, v111
	v_fma_f32 v101, v111, v101, 1.0
	v_mul_f32_e32 v101, v111, v101
	v_mul_f32_e32 v101, 0xc0135761, v101
	v_exp_f32_e32 v101, v101
	v_pk_mul_f32 v[108:109], v[108:109], v[102:103]
	v_add_f32_e32 v101, 1.0, v101
	v_rcp_f32_e32 v115, v101
	v_mul_f32_e32 v101, 0x3d372713, v104
	v_fma_f32 v101, v104, v101, 1.0
	v_mul_f32_e32 v101, v104, v101
	v_mul_f32_e32 v101, 0xc0135761, v101
	v_exp_f32_e32 v101, v101
	v_pk_mul_f32 v[110:111], v[110:111], v[114:115]
	v_add_f32_e32 v101, 1.0, v101
	v_rcp_f32_e32 v116, v101
	v_mul_f32_e32 v101, 0x3d372713, v106
	v_fma_f32 v101, v106, v101, 1.0
	v_mul_f32_e32 v101, v106, v101
	v_mul_f32_e32 v101, 0xc0135761, v101
	v_exp_f32_e32 v101, v101
	s_nop 0
	v_add_f32_e32 v101, 1.0, v101
	v_rcp_f32_e32 v118, v101
	v_mul_f32_e32 v101, 0x3d372713, v105
	v_fma_f32 v101, v105, v101, 1.0
	v_mul_f32_e32 v101, v105, v101
	v_mul_f32_e32 v101, 0xc0135761, v101
	v_exp_f32_e32 v101, v101
	s_nop 0
	v_add_f32_e32 v101, 1.0, v101
	v_rcp_f32_e32 v117, v101
	v_mul_f32_e32 v101, 0x3d372713, v107
	v_fma_f32 v101, v107, v101, 1.0
	v_mul_f32_e32 v101, v107, v101
	v_mul_f32_e32 v101, 0xc0135761, v101
	v_exp_f32_e32 v101, v101
	v_pk_mul_f32 v[104:105], v[104:105], v[116:117]
	v_add_f32_e32 v101, 1.0, v101
	v_rcp_f32_e32 v119, v101
	s_nop 0
	v_pk_mul_f32 v[106:107], v[106:107], v[118:119]

; __device__ __forceinline__ float fexp2(float x) { return __builtin_amdgcn_exp2f(x); }
; __device__ __forceinline__ float frcp(float x) { return __builtin_amdgcn_rcpf(x); }
; __device__ __forceinline__ float gelu_tanh(float x) { const float in = x * (1.0f + 0.044715f * x * x); return x * frcp(1.0f + fexp2(-2.302208198f * in)); }
; __device__ __forceinline__ float row_rs(const float* PS, int row, int fq) { return rsqrtf(PS[row] * (1.0f / 1024.0f) + 1e-6f); }
;     __device__ __forceinline__ static unsigned q8(float s) { return (unsigned)fminf(s * 256.0f, 255.0f); }
;     __device__ __forceinline__ void operator()(const f32x4 (&acc)[2][2][4][2], const Unit& u, int wr, int wc, int fr, int fq) const {
;     ...
;             for (int m = 0; m < 4; ++m) { const int row = row0 + ai * HALF + m * 16; const float rs = row_rs(PS, row, fq);
;                 if (sig) {
;                     unsigned w[4];
; #pragma unroll
;                     for (int bj = 0; bj < 2; ++bj) { const f32x4 v0 = acc[ai][bj][m][0] * rs, v1 = acc[ai][bj][m][1] * rs; unsigned b[8];
; #pragma unroll
;                         for (int j = 0; j < 4; ++j) { b[j] = q8(frcp(1.0f + fexp2(-1.4426950409f * v0[j]))); b[4 + j] = q8(frcp(1.0f + fexp2(-1.4426950409f * v1[j]))); }
;                         w[2 * bj] = b[0] | (b[1] << 8) | (b[2] << 16) | (b[3] << 24); w[2 * bj + 1] = b[4] | (b[5] << 8) | (b[6] << 16) | (b[7] << 24); }
;                     u32x4 wv; wv.x = w[0]; wv.y = w[1]; wv.z = w[2]; wv.w = w[3];
;                     *(u32x4*)((unsigned char*)O + (size_t)row * (2 * ldc) + 3584 + 2 * ((u.pn - 7) * 128 + wc * 32 + 8 * fq)) = wv;
;                 } else {
;                     bf16_t* rowp = O + (size_t)row * ldc + col0;
; #pragma unroll
;                     for (int bj = 0; bj < 2; ++bj) { f32x4 v0 = acc[ai][bj][m][0] * rs, v1 = acc[ai][bj][m][1] * rs;
;                         if (act) {
; #pragma unroll
;                             for (int j = 0; j < 4; ++j) { v0[j] = gelu_tanh(v0[j]); v1[j] = gelu_tanh(v1[j]); } }
.LBB0_329:
	v_mov_b32_e32 v84, v229
	v_or_b32_e32 v96, 48, v146
	s_and_b64 vcc, exec, s[44:45]
	s_mov_b64 s[18:19], -1
	v_fmamk_f32 v84, v84, 0x3a800000, v196
	v_mul_f32_e32 v85, 0x4b800000, v84
	v_cmp_gt_f32_e64 s[46:47], s13, v84
	s_nop 1
	v_cndmask_b32_e64 v84, v84, v85, s[46:47]
	v_rsq_f32_e32 v84, v84
	s_nop 0
	v_mul_f32_e32 v85, 0x45800000, v84
	v_cndmask_b32_e64 v84, v84, v85, s[46:47]
	s_cbranch_vccnz .LBB0_335
	v_pk_mul_f32 v[88:89], v[82:83], v[84:85] op_sel_hi:[1,0]
	v_pk_mul_f32 v[92:93], v[80:81], v[84:85] op_sel_hi:[1,0]
	v_pk_mul_f32 v[90:91], v[78:79], v[84:85] op_sel_hi:[1,0]
	s_and_b64 vcc, exec, s[42:43]
	v_pk_mul_f32 v[94:95], v[76:77], v[84:85] op_sel_hi:[1,0]
	s_cbranch_vccnz .LBB0_332
	v_mul_f32_e32 v85, 0x3d372713, v92
	v_fma_f32 v85, v92, v85, 1.0
	v_mul_f32_e32 v85, v92, v85
	v_mul_f32_e32 v85, 0xc0135761, v85
	v_exp_f32_e32 v85, v85
	s_nop 0
	v_add_f32_e32 v85, 1.0, v85
	v_rcp_f32_e32 v86, v85
	v_mul_f32_e32 v85, 0x3d372713, v94
	v_fma_f32 v85, v94, v85, 1.0
	v_mul_f32_e32 v85, v94, v85
	v_mul_f32_e32 v85, 0xc0135761, v85
	v_exp_f32_e32 v85, v85
	s_nop 0
	v_add_f32_e32 v85, 1.0, v85
	v_rcp_f32_e32 v98, v85
	v_mul_f32_e32 v85, 0x3d372713, v93
	v_fma_f32 v85, v93, v85, 1.0
	v_mul_f32_e32 v85, v93, v85
	v_mul_f32_e32 v85, 0xc0135761, v85
	v_exp_f32_e32 v85, v85
	s_nop 0
	v_add_f32_e32 v85, 1.0, v85
	v_rcp_f32_e32 v87, v85
	v_mul_f32_e32 v85, 0x3d372713, v95
	v_fma_f32 v85, v95, v85, 1.0
	v_mul_f32_e32 v85, v95, v85
	v_mul_f32_e32 v85, 0xc0135761, v85
	v_exp_f32_e32 v85, v85
	v_pk_mul_f32 v[92:93], v[92:93], v[86:87]
	v_add_f32_e32 v85, 1.0, v85
	v_rcp_f32_e32 v99, v85
	v_mul_f32_e32 v85, 0x3d372713, v88
	v_fma_f32 v85, v88, v85, 1.0
	v_mul_f32_e32 v85, v88, v85
	v_mul_f32_e32 v85, 0xc0135761, v85
	v_exp_f32_e32 v85, v85
	v_pk_mul_f32 v[94:95], v[94:95], v[98:99]
	v_add_f32_e32 v85, 1.0, v85
	v_rcp_f32_e32 v100, v85
	v_mul_f32_e32 v85, 0x3d372713, v90
	v_fma_f32 v85, v90, v85, 1.0
	v_mul_f32_e32 v85, v90, v85
	v_mul_f32_e32 v85, 0xc0135761, v85
	v_exp_f32_e32 v85, v85
	s_nop 0
	v_add_f32_e32 v85, 1.0, v85
	v_rcp_f32_e32 v102, v85
	v_mul_f32_e32 v85, 0x3d372713, v89
	v_fma_f32 v85, v89, v85, 1.0
	v_mul_f32_e32 v85, v89, v85
	v_mul_f32_e32 v85, 0xc0135761, v85
	v_exp_f32_e32 v85, v85
	s_nop 0
	v_add_f32_e32 v85, 1.0, v85
	v_rcp_f32_e32 v101, v85
	v_mul_f32_e32 v85, 0x3d372713, v91
	v_fma_f32 v85, v91, v85, 1.0
	v_mul_f32_e32 v85, v91, v85
	v_mul_f32_e32 v85, 0xc0135761, v85
	v_exp_f32_e32 v85, v85
	v_pk_mul_f32 v[88:89], v[88:89], v[100:101]
	v_add_f32_e32 v85, 1.0, v85
	v_rcp_f32_e32 v103, v85
	s_nop 0
	v_pk_mul_f32 v[90:91], v[90:91], v[102:103]

; __device__ __forceinline__ float fexp2(float x) { return __builtin_amdgcn_exp2f(x); }
; __device__ __forceinline__ float frcp(float x) { return __builtin_amdgcn_rcpf(x); }
; __device__ __forceinline__ float gelu_tanh(float x) { const float in = x * (1.0f + 0.044715f * x * x); return x * frcp(1.0f + fexp2(-2.302208198f * in)); }
; __device__ __forceinline__ float row_rs(const float* PS, int row, int fq) { return rsqrtf(PS[row] * (1.0f / 1024.0f) + 1e-6f); }
;     __device__ __forceinline__ static unsigned q8(float s) { return (unsigned)fminf(s * 256.0f, 255.0f); }
;     __device__ __forceinline__ void operator()(const f32x4 (&acc)[2][2][4][2], const Unit& u, int wr, int wc, int fr, int fq) const {
;     ...
;             for (int m = 0; m < 4; ++m) { const int row = row0 + ai * HALF + m * 16; const float rs = row_rs(PS, row, fq);
;                 if (sig) {
;                     unsigned w[4];
; #pragma unroll
;                     for (int bj = 0; bj < 2; ++bj) { const f32x4 v0 = acc[ai][bj][m][0] * rs, v1 = acc[ai][bj][m][1] * rs; unsigned b[8];
; #pragma unroll
;                         for (int j = 0; j < 4; ++j) { b[j] = q8(frcp(1.0f + fexp2(-1.4426950409f * v0[j]))); b[4 + j] = q8(frcp(1.0f + fexp2(-1.4426950409f * v1[j]))); }
;                         w[2 * bj] = b[0] | (b[1] << 8) | (b[2] << 16) | (b[3] << 24); w[2 * bj + 1] = b[4] | (b[5] << 8) | (b[6] << 16) | (b[7] << 24); }
;                     u32x4 wv; wv.x = w[0]; wv.y = w[1]; wv.z = w[2]; wv.w = w[3];
;                     *(u32x4*)((unsigned char*)O + (size_t)row * (2 * ldc) + 3584 + 2 * ((u.pn - 7) * 128 + wc * 32 + 8 * fq)) = wv;
;                 } else {
;                     bf16_t* rowp = O + (size_t)row * ldc + col0;
; #pragma unroll
;                     for (int bj = 0; bj < 2; ++bj) { f32x4 v0 = acc[ai][bj][m][0] * rs, v1 = acc[ai][bj][m][1] * rs;
;                         if (act) {
; #pragma unroll
;                             for (int j = 0; j < 4; ++j) { v0[j] = gelu_tanh(v0[j]); v1[j] = gelu_tanh(v1[j]); } }
.LBB0_337:
	v_mov_b32_e32 v68, v230
	v_add_u32_e32 v80, 0x80, v146
	s_and_b64 vcc, exec, s[44:45]
	s_mov_b64 s[18:19], -1
	v_fmamk_f32 v68, v68, 0x3a800000, v196
	v_mul_f32_e32 v69, 0x4b800000, v68
	v_cmp_gt_f32_e64 s[46:47], s13, v68
	s_nop 1
	v_cndmask_b32_e64 v68, v68, v69, s[46:47]
	v_rsq_f32_e32 v68, v68
	s_nop 0
	v_mul_f32_e32 v69, 0x45800000, v68
	v_cndmask_b32_e64 v68, v68, v69, s[46:47]
	s_cbranch_vccnz .LBB0_343
	v_pk_mul_f32 v[72:73], v[66:67], v[68:69] op_sel_hi:[1,0]
	v_pk_mul_f32 v[76:77], v[64:65], v[68:69] op_sel_hi:[1,0]
	v_pk_mul_f32 v[74:75], v[62:63], v[68:69] op_sel_hi:[1,0]
	s_and_b64 vcc, exec, s[42:43]
	v_pk_mul_f32 v[78:79], v[60:61], v[68:69] op_sel_hi:[1,0]
	s_cbranch_vccnz .LBB0_340
	v_mul_f32_e32 v69, 0x3d372713, v76
	v_fma_f32 v69, v76, v69, 1.0
	v_mul_f32_e32 v69, v76, v69
	v_mul_f32_e32 v69, 0xc0135761, v69
	v_exp_f32_e32 v69, v69
	s_nop 0
	v_add_f32_e32 v69, 1.0, v69
	v_rcp_f32_e32 v70, v69
	v_mul_f32_e32 v69, 0x3d372713, v78
	v_fma_f32 v69, v78, v69, 1.0
	v_mul_f32_e32 v69, v78, v69
	v_mul_f32_e32 v69, 0xc0135761, v69
	v_exp_f32_e32 v69, v69
	s_nop 0
	v_add_f32_e32 v69, 1.0, v69
	v_rcp_f32_e32 v82, v69
	v_mul_f32_e32 v69, 0x3d372713, v77
	v_fma_f32 v69, v77, v69, 1.0
	v_mul_f32_e32 v69, v77, v69
	v_mul_f32_e32 v69, 0xc0135761, v69
	v_exp_f32_e32 v69, v69
	s_nop 0
	v_add_f32_e32 v69, 1.0, v69
	v_rcp_f32_e32 v71, v69
	v_mul_f32_e32 v69, 0x3d372713, v79
	v_fma_f32 v69, v79, v69, 1.0
	v_mul_f32_e32 v69, v79, v69
	v_mul_f32_e32 v69, 0xc0135761, v69
	v_exp_f32_e32 v69, v69
	v_pk_mul_f32 v[76:77], v[76:77], v[70:71]
	v_add_f32_e32 v69, 1.0, v69
	v_rcp_f32_e32 v83, v69
	v_mul_f32_e32 v69, 0x3d372713, v72
	v_fma_f32 v69, v72, v69, 1.0
	v_mul_f32_e32 v69, v72, v69
	v_mul_f32_e32 v69, 0xc0135761, v69
	v_exp_f32_e32 v69, v69
	v_pk_mul_f32 v[78:79], v[78:79], v[82:83]
	v_add_f32_e32 v69, 1.0, v69
	v_rcp_f32_e32 v84, v69
	v_mul_f32_e32 v69, 0x3d372713, v74
	v_fma_f32 v69, v74, v69, 1.0
	v_mul_f32_e32 v69, v74, v69
	v_mul_f32_e32 v69, 0xc0135761, v69
	v_exp_f32_e32 v69, v69
	s_nop 0
	v_add_f32_e32 v69, 1.0, v69
	v_rcp_f32_e32 v86, v69
	v_mul_f32_e32 v69, 0x3d372713, v73
	v_fma_f32 v69, v73, v69, 1.0
	v_mul_f32_e32 v69, v73, v69
	v_mul_f32_e32 v69, 0xc0135761, v69
	v_exp_f32_e32 v69, v69
	s_nop 0
	v_add_f32_e32 v69, 1.0, v69
	v_rcp_f32_e32 v85, v69
	v_mul_f32_e32 v69, 0x3d372713, v75
	v_fma_f32 v69, v75, v69, 1.0
	v_mul_f32_e32 v69, v75, v69
	v_mul_f32_e32 v69, 0xc0135761, v69
	v_exp_f32_e32 v69, v69
	v_pk_mul_f32 v[72:73], v[72:73], v[84:85]
	v_add_f32_e32 v69, 1.0, v69
	v_rcp_f32_e32 v87, v69
	s_nop 0
	v_pk_mul_f32 v[74:75], v[74:75], v[86:87]

; __device__ __forceinline__ float fexp2(float x) { return __builtin_amdgcn_exp2f(x); }
; __device__ __forceinline__ float frcp(float x) { return __builtin_amdgcn_rcpf(x); }
; __device__ __forceinline__ float gelu_tanh(float x) { const float in = x * (1.0f + 0.044715f * x * x); return x * frcp(1.0f + fexp2(-2.302208198f * in)); }
; __device__ __forceinline__ float row_rs(const float* PS, int row, int fq) { return rsqrtf(PS[row] * (1.0f / 1024.0f) + 1e-6f); }
;     __device__ __forceinline__ static unsigned q8(float s) { return (unsigned)fminf(s * 256.0f, 255.0f); }
;     __device__ __forceinline__ void operator()(const f32x4 (&acc)[2][2][4][2], const Unit& u, int wr, int wc, int fr, int fq) const {
;     ...
;             for (int m = 0; m < 4; ++m) { const int row = row0 + ai * HALF + m * 16; const float rs = row_rs(PS, row, fq);
;                 if (sig) {
;                     unsigned w[4];
; #pragma unroll
;                     for (int bj = 0; bj < 2; ++bj) { const f32x4 v0 = acc[ai][bj][m][0] * rs, v1 = acc[ai][bj][m][1] * rs; unsigned b[8];
; #pragma unroll
;                         for (int j = 0; j < 4; ++j) { b[j] = q8(frcp(1.0f + fexp2(-1.4426950409f * v0[j]))); b[4 + j] = q8(frcp(1.0f + fexp2(-1.4426950409f * v1[j]))); }
;                         w[2 * bj] = b[0] | (b[1] << 8) | (b[2] << 16) | (b[3] << 24); w[2 * bj + 1] = b[4] | (b[5] << 8) | (b[6] << 16) | (b[7] << 24); }
;                     u32x4 wv; wv.x = w[0]; wv.y = w[1]; wv.z = w[2]; wv.w = w[3];
;                     *(u32x4*)((unsigned char*)O + (size_t)row * (2 * ldc) + 3584 + 2 * ((u.pn - 7) * 128 + wc * 32 + 8 * fq)) = wv;
;                 } else {
;                     bf16_t* rowp = O + (size_t)row * ldc + col0;
; #pragma unroll
;                     for (int bj = 0; bj < 2; ++bj) { f32x4 v0 = acc[ai][bj][m][0] * rs, v1 = acc[ai][bj][m][1] * rs;
;                         if (act) {
; #pragma unroll
;                             for (int j = 0; j < 4; ++j) { v0[j] = gelu_tanh(v0[j]); v1[j] = gelu_tanh(v1[j]); } }
.LBB0_345:
	v_mov_b32_e32 v52, v231
	v_add_u32_e32 v64, 0x90, v146
	s_and_b64 vcc, exec, s[44:45]
	s_mov_b64 s[18:19], -1
	v_fmamk_f32 v52, v52, 0x3a800000, v196
	v_mul_f32_e32 v53, 0x4b800000, v52
	v_cmp_gt_f32_e64 s[46:47], s13, v52
	s_nop 1
	v_cndmask_b32_e64 v52, v52, v53, s[46:47]
	v_rsq_f32_e32 v52, v52
	s_nop 0
	v_mul_f32_e32 v53, 0x45800000, v52
	v_cndmask_b32_e64 v52, v52, v53, s[46:47]
	s_cbranch_vccnz .LBB0_351
	v_pk_mul_f32 v[56:57], v[50:51], v[52:53] op_sel_hi:[1,0]
	v_pk_mul_f32 v[60:61], v[48:49], v[52:53] op_sel_hi:[1,0]
	v_pk_mul_f32 v[58:59], v[46:47], v[52:53] op_sel_hi:[1,0]
	s_and_b64 vcc, exec, s[42:43]
	v_pk_mul_f32 v[62:63], v[44:45], v[52:53] op_sel_hi:[1,0]
	s_cbranch_vccnz .LBB0_348
	v_mul_f32_e32 v53, 0x3d372713, v60
	v_fma_f32 v53, v60, v53, 1.0
	v_mul_f32_e32 v53, v60, v53
	v_mul_f32_e32 v53, 0xc0135761, v53
	v_exp_f32_e32 v53, v53
	s_nop 0
	v_add_f32_e32 v53, 1.0, v53
	v_rcp_f32_e32 v54, v53
	v_mul_f32_e32 v53, 0x3d372713, v62
	v_fma_f32 v53, v62, v53, 1.0
	v_mul_f32_e32 v53, v62, v53
	v_mul_f32_e32 v53, 0xc0135761, v53
	v_exp_f32_e32 v53, v53
	s_nop 0
	v_add_f32_e32 v53, 1.0, v53
	v_rcp_f32_e32 v66, v53
	v_mul_f32_e32 v53, 0x3d372713, v61
	v_fma_f32 v53, v61, v53, 1.0
	v_mul_f32_e32 v53, v61, v53
	v_mul_f32_e32 v53, 0xc0135761, v53
	v_exp_f32_e32 v53, v53
	s_nop 0
	v_add_f32_e32 v53, 1.0, v53
	v_rcp_f32_e32 v55, v53
	v_mul_f32_e32 v53, 0x3d372713, v63
	v_fma_f32 v53, v63, v53, 1.0
	v_mul_f32_e32 v53, v63, v53
	v_mul_f32_e32 v53, 0xc0135761, v53
	v_exp_f32_e32 v53, v53
	v_pk_mul_f32 v[60:61], v[60:61], v[54:55]
	v_add_f32_e32 v53, 1.0, v53
	v_rcp_f32_e32 v67, v53
	v_mul_f32_e32 v53, 0x3d372713, v56
	v_fma_f32 v53, v56, v53, 1.0
	v_mul_f32_e32 v53, v56, v53
	v_mul_f32_e32 v53, 0xc0135761, v53
	v_exp_f32_e32 v53, v53
	v_pk_mul_f32 v[62:63], v[62:63], v[66:67]
	v_add_f32_e32 v53, 1.0, v53
	v_rcp_f32_e32 v68, v53
	v_mul_f32_e32 v53, 0x3d372713, v58
	v_fma_f32 v53, v58, v53, 1.0
	v_mul_f32_e32 v53, v58, v53
	v_mul_f32_e32 v53, 0xc0135761, v53
	v_exp_f32_e32 v53, v53
	s_nop 0
	v_add_f32_e32 v53, 1.0, v53
	v_rcp_f32_e32 v70, v53
	v_mul_f32_e32 v53, 0x3d372713, v57
	v_fma_f32 v53, v57, v53, 1.0
	v_mul_f32_e32 v53, v57, v53
	v_mul_f32_e32 v53, 0xc0135761, v53
	v_exp_f32_e32 v53, v53
	s_nop 0
	v_add_f32_e32 v53, 1.0, v53
	v_rcp_f32_e32 v69, v53
	v_mul_f32_e32 v53, 0x3d372713, v59
	v_fma_f32 v53, v59, v53, 1.0
	v_mul_f32_e32 v53, v59, v53
	v_mul_f32_e32 v53, 0xc0135761, v53
	v_exp_f32_e32 v53, v53
	v_pk_mul_f32 v[56:57], v[56:57], v[68:69]
	v_add_f32_e32 v53, 1.0, v53
	v_rcp_f32_e32 v71, v53
	s_nop 0
	v_pk_mul_f32 v[58:59], v[58:59], v[70:71]

; __device__ __forceinline__ float fexp2(float x) { return __builtin_amdgcn_exp2f(x); }
; __device__ __forceinline__ float frcp(float x) { return __builtin_amdgcn_rcpf(x); }
; __device__ __forceinline__ float gelu_tanh(float x) { const float in = x * (1.0f + 0.044715f * x * x); return x * frcp(1.0f + fexp2(-2.302208198f * in)); }
; __device__ __forceinline__ float row_rs(const float* PS, int row, int fq) { return rsqrtf(PS[row] * (1.0f / 1024.0f) + 1e-6f); }
;     __device__ __forceinline__ static unsigned q8(float s) { return (unsigned)fminf(s * 256.0f, 255.0f); }
;     __device__ __forceinline__ void operator()(const f32x4 (&acc)[2][2][4][2], const Unit& u, int wr, int wc, int fr, int fq) const {
;     ...
;             for (int m = 0; m < 4; ++m) { const int row = row0 + ai * HALF + m * 16; const float rs = row_rs(PS, row, fq);
;                 if (sig) {
;                     unsigned w[4];
; #pragma unroll
;                     for (int bj = 0; bj < 2; ++bj) { const f32x4 v0 = acc[ai][bj][m][0] * rs, v1 = acc[ai][bj][m][1] * rs; unsigned b[8];
; #pragma unroll
;                         for (int j = 0; j < 4; ++j) { b[j] = q8(frcp(1.0f + fexp2(-1.4426950409f * v0[j]))); b[4 + j] = q8(frcp(1.0f + fexp2(-1.4426950409f * v1[j]))); }
;                         w[2 * bj] = b[0] | (b[1] << 8) | (b[2] << 16) | (b[3] << 24); w[2 * bj + 1] = b[4] | (b[5] << 8) | (b[6] << 16) | (b[7] << 24); }
;                     u32x4 wv; wv.x = w[0]; wv.y = w[1]; wv.z = w[2]; wv.w = w[3];
;                     *(u32x4*)((unsigned char*)O + (size_t)row * (2 * ldc) + 3584 + 2 * ((u.pn - 7) * 128 + wc * 32 + 8 * fq)) = wv;
;                 } else {
;                     bf16_t* rowp = O + (size_t)row * ldc + col0;
; #pragma unroll
;                     for (int bj = 0; bj < 2; ++bj) { f32x4 v0 = acc[ai][bj][m][0] * rs, v1 = acc[ai][bj][m][1] * rs;
;                         if (act) {
; #pragma unroll
;                             for (int j = 0; j < 4; ++j) { v0[j] = gelu_tanh(v0[j]); v1[j] = gelu_tanh(v1[j]); } }
.LBB0_353:
	v_mov_b32_e32 v36, v232
	v_add_u32_e32 v48, 0xa0, v146
	s_and_b64 vcc, exec, s[44:45]
	s_mov_b64 s[18:19], -1
	v_fmamk_f32 v36, v36, 0x3a800000, v196
	v_mul_f32_e32 v37, 0x4b800000, v36
	v_cmp_gt_f32_e64 s[46:47], s13, v36
	s_nop 1
	v_cndmask_b32_e64 v36, v36, v37, s[46:47]
	v_rsq_f32_e32 v36, v36
	s_nop 0
	v_mul_f32_e32 v37, 0x45800000, v36
	v_cndmask_b32_e64 v36, v36, v37, s[46:47]
	s_cbranch_vccnz .LBB0_359
	v_pk_mul_f32 v[40:41], v[34:35], v[36:37] op_sel_hi:[1,0]
	v_pk_mul_f32 v[44:45], v[32:33], v[36:37] op_sel_hi:[1,0]
	v_pk_mul_f32 v[42:43], v[30:31], v[36:37] op_sel_hi:[1,0]
	s_and_b64 vcc, exec, s[42:43]
	v_pk_mul_f32 v[46:47], v[28:29], v[36:37] op_sel_hi:[1,0]
	s_cbranch_vccnz .LBB0_356
	v_mul_f32_e32 v37, 0x3d372713, v44
	v_fma_f32 v37, v44, v37, 1.0
	v_mul_f32_e32 v37, v44, v37
	v_mul_f32_e32 v37, 0xc0135761, v37
	v_exp_f32_e32 v37, v37
	s_nop 0
	v_add_f32_e32 v37, 1.0, v37
	v_rcp_f32_e32 v38, v37
	v_mul_f32_e32 v37, 0x3d372713, v46
	v_fma_f32 v37, v46, v37, 1.0
	v_mul_f32_e32 v37, v46, v37
	v_mul_f32_e32 v37, 0xc0135761, v37
	v_exp_f32_e32 v37, v37
	s_nop 0
	v_add_f32_e32 v37, 1.0, v37
	v_rcp_f32_e32 v50, v37
	v_mul_f32_e32 v37, 0x3d372713, v45
	v_fma_f32 v37, v45, v37, 1.0
	v_mul_f32_e32 v37, v45, v37
	v_mul_f32_e32 v37, 0xc0135761, v37
	v_exp_f32_e32 v37, v37
	s_nop 0
	v_add_f32_e32 v37, 1.0, v37
	v_rcp_f32_e32 v39, v37
	v_mul_f32_e32 v37, 0x3d372713, v47
	v_fma_f32 v37, v47, v37, 1.0
	v_mul_f32_e32 v37, v47, v37
	v_mul_f32_e32 v37, 0xc0135761, v37
	v_exp_f32_e32 v37, v37
	v_pk_mul_f32 v[44:45], v[44:45], v[38:39]
	v_add_f32_e32 v37, 1.0, v37
	v_rcp_f32_e32 v51, v37
	v_mul_f32_e32 v37, 0x3d372713, v40
	v_fma_f32 v37, v40, v37, 1.0
	v_mul_f32_e32 v37, v40, v37
	v_mul_f32_e32 v37, 0xc0135761, v37
	v_exp_f32_e32 v37, v37
	v_pk_mul_f32 v[46:47], v[46:47], v[50:51]
	v_add_f32_e32 v37, 1.0, v37
	v_rcp_f32_e32 v52, v37
	v_mul_f32_e32 v37, 0x3d372713, v42
	v_fma_f32 v37, v42, v37, 1.0
	v_mul_f32_e32 v37, v42, v37
	v_mul_f32_e32 v37, 0xc0135761, v37
	v_exp_f32_e32 v37, v37
	s_nop 0
	v_add_f32_e32 v37, 1.0, v37
	v_rcp_f32_e32 v54, v37
	v_mul_f32_e32 v37, 0x3d372713, v41
	v_fma_f32 v37, v41, v37, 1.0
	v_mul_f32_e32 v37, v41, v37
	v_mul_f32_e32 v37, 0xc0135761, v37
	v_exp_f32_e32 v37, v37
	s_nop 0
	v_add_f32_e32 v37, 1.0, v37
	v_rcp_f32_e32 v53, v37
	v_mul_f32_e32 v37, 0x3d372713, v43
	v_fma_f32 v37, v43, v37, 1.0
	v_mul_f32_e32 v37, v43, v37
	v_mul_f32_e32 v37, 0xc0135761, v37
	v_exp_f32_e32 v37, v37
	v_pk_mul_f32 v[40:41], v[40:41], v[52:53]
	v_add_f32_e32 v37, 1.0, v37
	v_rcp_f32_e32 v55, v37
	s_nop 0
	v_pk_mul_f32 v[42:43], v[42:43], v[54:55]

; __device__ __forceinline__ float row_rs(const float* PS, int row, int fq) { return rsqrtf(PS[row] * (1.0f / 1024.0f) + 1e-6f); }
;     __device__ __forceinline__ void operator()(const f32x4 (&acc)[2][2][4][2], const Unit& u, int wr, int wc, int fr, int fq) const {
;     ...
;             for (int m = 0; m < 4; ++m) { const int row = row0 + ai * HALF + m * 16; const float rs = row_rs(PS, row, fq);
;                 if (sig) {
.LBB0_361:
	v_mov_b32_e32 v20, v233
	v_add_u32_e32 v32, 0xb0, v146
	s_and_b64 vcc, exec, s[44:45]
	s_mov_b64 s[18:19], -1
	v_fmamk_f32 v20, v20, 0x3a800000, v196
	v_mul_f32_e32 v21, 0x4b800000, v20
	v_cmp_gt_f32_e64 s[46:47], s13, v20
	s_nop 1
	v_cndmask_b32_e64 v20, v20, v21, s[46:47]
	v_rsq_f32_e32 v20, v20
	s_nop 0
	v_mul_f32_e32 v21, 0x45800000, v20
	v_cndmask_b32_e64 v20, v20, v21, s[46:47]
	s_cbranch_vccz .LBB0_364
	s_and_b64 vcc, exec, s[18:19]
	s_cbranch_vccnz .LBB0_369
